# v50 + w_out K-loop back-edge rotation; gate/up and w_in K-loops run their counter update and exit test ahead of the loop-back barrier
# baseline (speedup 1.0000x reference)
.LBB0_289:
	ds_read_b128 v[134:137], v161
	ds_read_b128 v[138:141], v161 offset:1024
	ds_read_b128 v[142:145], v161 offset:2048
	ds_read_b128 v[146:149], v161 offset:3072
	ds_read_b128 v[150:153], v162
	ds_read_b128 v[166:169], v162 offset:1024
	ds_read_b128 v[170:173], v162 offset:2048
	ds_read_b128 v[174:177], v162 offset:3072
	s_add_i32 s39, s78, 0xfffc0080
	s_cmp_eq_u32 s80, 12
	s_cselect_b32 s88, s18, s39
	s_cselect_b32 s83, s19, s79
	s_or_b32 s82, s88, 0x80
	s_mov_b32 m0, s59
	ds_read_b128 v[178:181], v163
	ds_read_b128 v[182:185], v163 offset:1024
	ds_read_b128 v[186:189], v163 offset:2048
	ds_read_b128 v[190:193], v163 offset:3072
	ds_read_b128 v[194:197], v163 offset:4096
	ds_read_b128 v[198:201], v163 offset:5120
	ds_read_b128 v[202:205], v163 offset:6144
	ds_read_b128 v[206:209], v163 offset:7168
	buffer_load_dwordx4 v1, s[28:31], s78 offen lds
	s_mov_b32 m0, s60
	s_nop 0
	buffer_load_dwordx4 v155, s[28:31], s78 offen lds
	s_waitcnt vmcnt(8)
	s_waitcnt lgkmcnt(0)
	s_barrier
	s_setprio 1
	s_waitcnt lgkmcnt(0)
	v_mfma_i32_16x16x64_i8 v[126:129], v[134:137], v[178:181], v[126:129]
	v_mfma_i32_16x16x64_i8 v[122:125], v[142:145], v[178:181], v[122:125]
	v_mfma_i32_16x16x64_i8 v[110:113], v[134:137], v[186:189], v[110:113]
	v_mfma_i32_16x16x64_i8 v[106:109], v[142:145], v[186:189], v[106:109]
	v_mfma_i32_16x16x64_i8 v[94:97], v[134:137], v[194:197], v[94:97]
	v_mfma_i32_16x16x64_i8 v[90:93], v[142:145], v[194:197], v[90:93]
	v_mfma_i32_16x16x64_i8 v[78:81], v[134:137], v[202:205], v[78:81]
	v_mfma_i32_16x16x64_i8 v[74:77], v[142:145], v[202:205], v[74:77]
	v_mfma_i32_16x16x64_i8 v[126:129], v[138:141], v[182:185], v[126:129]
	v_mfma_i32_16x16x64_i8 v[122:125], v[146:149], v[182:185], v[122:125]
	v_mfma_i32_16x16x64_i8 v[110:113], v[138:141], v[190:193], v[110:113]
	v_mfma_i32_16x16x64_i8 v[106:109], v[146:149], v[190:193], v[106:109]
	v_mfma_i32_16x16x64_i8 v[94:97], v[138:141], v[198:201], v[94:97]
	v_mfma_i32_16x16x64_i8 v[90:93], v[146:149], v[198:201], v[90:93]
	v_mfma_i32_16x16x64_i8 v[78:81], v[138:141], v[206:209], v[78:81]
	v_mfma_i32_16x16x64_i8 v[74:77], v[146:149], v[206:209], v[74:77]
	s_setprio 0
	s_setprio 1
	v_mfma_i32_16x16x64_i8 v[118:121], v[150:153], v[178:181], v[118:121]
	v_mfma_i32_16x16x64_i8 v[114:117], v[170:173], v[178:181], v[114:117]
	v_mfma_i32_16x16x64_i8 v[102:105], v[150:153], v[186:189], v[102:105]
	v_mfma_i32_16x16x64_i8 v[98:101], v[170:173], v[186:189], v[98:101]
	v_mfma_i32_16x16x64_i8 v[86:89], v[150:153], v[194:197], v[86:89]
	v_mfma_i32_16x16x64_i8 v[82:85], v[170:173], v[194:197], v[82:85]
	v_mfma_i32_16x16x64_i8 v[70:73], v[150:153], v[202:205], v[70:73]
	v_mfma_i32_16x16x64_i8 v[66:69], v[170:173], v[202:205], v[66:69]
	v_mfma_i32_16x16x64_i8 v[118:121], v[166:169], v[182:185], v[118:121]
	v_mfma_i32_16x16x64_i8 v[114:117], v[174:177], v[182:185], v[114:117]
	v_mfma_i32_16x16x64_i8 v[102:105], v[166:169], v[190:193], v[102:105]
	v_mfma_i32_16x16x64_i8 v[98:101], v[174:177], v[190:193], v[98:101]
	v_mfma_i32_16x16x64_i8 v[86:89], v[166:169], v[198:201], v[86:89]
	v_mfma_i32_16x16x64_i8 v[82:85], v[174:177], v[198:201], v[82:85]
	v_mfma_i32_16x16x64_i8 v[70:73], v[166:169], v[206:209], v[70:73]
	v_mfma_i32_16x16x64_i8 v[66:69], v[174:177], v[206:209], v[66:69]
	s_setprio 0
	s_barrier
	s_mov_b32 m0, s35
	s_mov_b32 s39, s31
	ds_read_b128 v[178:181], v163 offset:16384
	ds_read_b128 v[182:185], v163 offset:17408
	ds_read_b128 v[186:189], v163 offset:18432
	ds_read_b128 v[190:193], v163 offset:19456
	ds_read_b128 v[194:197], v163 offset:20480
	ds_read_b128 v[198:201], v163 offset:21504
	ds_read_b128 v[202:205], v163 offset:22528
	ds_read_b128 v[206:209], v163 offset:23552
	buffer_load_dwordx4 v154, s[36:39], s83 offen lds
	s_mov_b32 m0, s40
	s_add_i32 s89, s83, 0x40000
	buffer_load_dwordx4 v156, s[36:39], s83 offen lds
	s_mov_b32 m0, s41
	s_nop 0
	buffer_load_dwordx4 v154, s[36:39], s89 offen lds
	s_mov_b32 m0, s43
	s_nop 0
	buffer_load_dwordx4 v156, s[36:39], s89 offen lds
	s_mov_b32 m0, s34
	s_nop 0
	buffer_load_dwordx4 v1, s[28:31], s88 offen lds
	s_mov_b32 m0, s44
	s_nop 0
	buffer_load_dwordx4 v155, s[28:31], s88 offen lds
	s_waitcnt vmcnt(8)
	s_waitcnt lgkmcnt(0)
	s_barrier
	s_setprio 1
	s_waitcnt lgkmcnt(0)
	v_mfma_i32_16x16x64_i8 v[62:65], v[134:137], v[178:181], v[62:65]
	v_mfma_i32_16x16x64_i8 v[58:61], v[142:145], v[178:181], v[58:61]
	s_waitcnt lgkmcnt(5)
	v_mfma_i32_16x16x64_i8 v[46:49], v[134:137], v[186:189], v[46:49]
	v_mfma_i32_16x16x64_i8 v[42:45], v[142:145], v[186:189], v[42:45]
	s_waitcnt lgkmcnt(3)
	v_mfma_i32_16x16x64_i8 v[30:33], v[134:137], v[194:197], v[30:33]
	v_mfma_i32_16x16x64_i8 v[26:29], v[142:145], v[194:197], v[26:29]
	s_waitcnt lgkmcnt(1)
	v_mfma_i32_16x16x64_i8 v[14:17], v[134:137], v[202:205], v[14:17]
	v_mfma_i32_16x16x64_i8 v[10:13], v[142:145], v[202:205], v[10:13]
	v_mfma_i32_16x16x64_i8 v[62:65], v[138:141], v[182:185], v[62:65]
	v_mfma_i32_16x16x64_i8 v[58:61], v[146:149], v[182:185], v[58:61]
	v_mfma_i32_16x16x64_i8 v[46:49], v[138:141], v[190:193], v[46:49]
	v_mfma_i32_16x16x64_i8 v[42:45], v[146:149], v[190:193], v[42:45]
	v_mfma_i32_16x16x64_i8 v[30:33], v[138:141], v[198:201], v[30:33]
	v_mfma_i32_16x16x64_i8 v[26:29], v[146:149], v[198:201], v[26:29]
	s_waitcnt lgkmcnt(0)
	v_mfma_i32_16x16x64_i8 v[14:17], v[138:141], v[206:209], v[14:17]
	v_mfma_i32_16x16x64_i8 v[10:13], v[146:149], v[206:209], v[10:13]
	s_setprio 0
	s_setprio 1
	v_mfma_i32_16x16x64_i8 v[54:57], v[150:153], v[178:181], v[54:57]
	v_mfma_i32_16x16x64_i8 v[50:53], v[170:173], v[178:181], v[50:53]
	v_mfma_i32_16x16x64_i8 v[38:41], v[150:153], v[186:189], v[38:41]
	v_mfma_i32_16x16x64_i8 v[34:37], v[170:173], v[186:189], v[34:37]
	v_mfma_i32_16x16x64_i8 v[22:25], v[150:153], v[194:197], v[22:25]
	v_mfma_i32_16x16x64_i8 v[18:21], v[170:173], v[194:197], v[18:21]
	v_mfma_i32_16x16x64_i8 v[6:9], v[150:153], v[202:205], v[6:9]
	v_mfma_i32_16x16x64_i8 v[2:5], v[170:173], v[202:205], v[2:5]
	v_mfma_i32_16x16x64_i8 v[54:57], v[166:169], v[182:185], v[54:57]
	v_mfma_i32_16x16x64_i8 v[50:53], v[174:177], v[182:185], v[50:53]
	v_mfma_i32_16x16x64_i8 v[38:41], v[166:169], v[190:193], v[38:41]
	v_mfma_i32_16x16x64_i8 v[34:37], v[174:177], v[190:193], v[34:37]
	v_mfma_i32_16x16x64_i8 v[22:25], v[166:169], v[198:201], v[22:25]
	v_mfma_i32_16x16x64_i8 v[18:21], v[174:177], v[198:201], v[18:21]
	v_mfma_i32_16x16x64_i8 v[6:9], v[166:169], v[206:209], v[6:9]
	v_mfma_i32_16x16x64_i8 v[2:5], v[174:177], v[206:209], v[2:5]
	s_setprio 0
	s_barrier
	ds_read_b128 v[134:137], v164
	ds_read_b128 v[138:141], v164 offset:1024
	ds_read_b128 v[142:145], v164 offset:2048
	ds_read_b128 v[146:149], v164 offset:3072
	ds_read_b128 v[150:153], v165
	ds_read_b128 v[166:169], v165 offset:1024
	ds_read_b128 v[170:173], v165 offset:2048
	ds_read_b128 v[174:177], v165 offset:3072
	s_add_i32 s88, s88, 0x40000
	s_mov_b32 m0, s45
	ds_read_b128 v[178:181], v163 offset:32768
	ds_read_b128 v[182:185], v163 offset:33792
	ds_read_b128 v[186:189], v163 offset:34816
	ds_read_b128 v[190:193], v163 offset:35840
	ds_read_b128 v[194:197], v163 offset:36864
	ds_read_b128 v[198:201], v163 offset:37888
	ds_read_b128 v[202:205], v163 offset:38912
	ds_read_b128 v[206:209], v163 offset:39936
	buffer_load_dwordx4 v1, s[28:31], s88 offen lds
	s_mov_b32 m0, s47
	s_nop 0
	buffer_load_dwordx4 v155, s[28:31], s88 offen lds
	s_waitcnt vmcnt(8)
	s_waitcnt lgkmcnt(0)
	s_barrier
	s_setprio 1
	s_waitcnt lgkmcnt(0)
	v_mfma_i32_16x16x64_i8 v[126:129], v[134:137], v[178:181], v[126:129]
	v_mfma_i32_16x16x64_i8 v[122:125], v[142:145], v[178:181], v[122:125]
	s_waitcnt lgkmcnt(5)
	v_mfma_i32_16x16x64_i8 v[110:113], v[134:137], v[186:189], v[110:113]
	v_mfma_i32_16x16x64_i8 v[106:109], v[142:145], v[186:189], v[106:109]
	s_waitcnt lgkmcnt(3)
	v_mfma_i32_16x16x64_i8 v[94:97], v[134:137], v[194:197], v[94:97]
	v_mfma_i32_16x16x64_i8 v[90:93], v[142:145], v[194:197], v[90:93]
	s_waitcnt lgkmcnt(1)
	v_mfma_i32_16x16x64_i8 v[78:81], v[134:137], v[202:205], v[78:81]
	v_mfma_i32_16x16x64_i8 v[74:77], v[142:145], v[202:205], v[74:77]
	v_mfma_i32_16x16x64_i8 v[126:129], v[138:141], v[182:185], v[126:129]
	v_mfma_i32_16x16x64_i8 v[122:125], v[146:149], v[182:185], v[122:125]
	v_mfma_i32_16x16x64_i8 v[110:113], v[138:141], v[190:193], v[110:113]
	v_mfma_i32_16x16x64_i8 v[106:109], v[146:149], v[190:193], v[106:109]
	v_mfma_i32_16x16x64_i8 v[94:97], v[138:141], v[198:201], v[94:97]
	v_mfma_i32_16x16x64_i8 v[90:93], v[146:149], v[198:201], v[90:93]
	s_waitcnt lgkmcnt(0)
	v_mfma_i32_16x16x64_i8 v[78:81], v[138:141], v[206:209], v[78:81]
	v_mfma_i32_16x16x64_i8 v[74:77], v[146:149], v[206:209], v[74:77]
	s_setprio 0
	s_setprio 1
	v_mfma_i32_16x16x64_i8 v[118:121], v[150:153], v[178:181], v[118:121]
	v_mfma_i32_16x16x64_i8 v[114:117], v[170:173], v[178:181], v[114:117]
	v_mfma_i32_16x16x64_i8 v[102:105], v[150:153], v[186:189], v[102:105]
	v_mfma_i32_16x16x64_i8 v[98:101], v[170:173], v[186:189], v[98:101]
	v_mfma_i32_16x16x64_i8 v[86:89], v[150:153], v[194:197], v[86:89]
	v_mfma_i32_16x16x64_i8 v[82:85], v[170:173], v[194:197], v[82:85]
	v_mfma_i32_16x16x64_i8 v[70:73], v[150:153], v[202:205], v[70:73]
	v_mfma_i32_16x16x64_i8 v[66:69], v[170:173], v[202:205], v[66:69]
	v_mfma_i32_16x16x64_i8 v[118:121], v[166:169], v[182:185], v[118:121]
	v_mfma_i32_16x16x64_i8 v[114:117], v[174:177], v[182:185], v[114:117]
	v_mfma_i32_16x16x64_i8 v[102:105], v[166:169], v[190:193], v[102:105]
	v_mfma_i32_16x16x64_i8 v[98:101], v[174:177], v[190:193], v[98:101]
	v_mfma_i32_16x16x64_i8 v[86:89], v[166:169], v[198:201], v[86:89]
	v_mfma_i32_16x16x64_i8 v[82:85], v[174:177], v[198:201], v[82:85]
	v_mfma_i32_16x16x64_i8 v[70:73], v[166:169], v[206:209], v[70:73]
	v_mfma_i32_16x16x64_i8 v[66:69], v[174:177], v[206:209], v[66:69]
	s_setprio 0
	s_barrier
	s_mov_b32 m0, s48
	s_or_b32 s88, s83, 0x80
	ds_read_b128 v[178:181], v163 offset:49152
	ds_read_b128 v[182:185], v163 offset:50176
	ds_read_b128 v[186:189], v163 offset:51200
	ds_read_b128 v[190:193], v163 offset:52224
	ds_read_b128 v[194:197], v163 offset:53248
	ds_read_b128 v[198:201], v163 offset:54272
	ds_read_b128 v[202:205], v163 offset:55296
	ds_read_b128 v[206:209], v163 offset:56320
	buffer_load_dwordx4 v154, s[36:39], s88 offen lds
	s_mov_b32 m0, s49
	s_add_i32 s83, s83, 0x40080
	buffer_load_dwordx4 v156, s[36:39], s88 offen lds
	s_mov_b32 m0, s53
	s_nop 0
	buffer_load_dwordx4 v154, s[36:39], s83 offen lds
	s_mov_b32 m0, s55
	s_nop 0
	buffer_load_dwordx4 v156, s[36:39], s83 offen lds
	s_mov_b32 m0, s51
	s_nop 0
	buffer_load_dwordx4 v1, s[28:31], s82 offen lds
	s_mov_b32 m0, s52
	s_nop 0
	buffer_load_dwordx4 v155, s[28:31], s82 offen lds
	s_waitcnt vmcnt(8)
	s_waitcnt lgkmcnt(0)
	s_barrier
	s_setprio 1
	s_waitcnt lgkmcnt(0)
	v_mfma_i32_16x16x64_i8 v[62:65], v[134:137], v[178:181], v[62:65]
	v_mfma_i32_16x16x64_i8 v[58:61], v[142:145], v[178:181], v[58:61]
	s_waitcnt lgkmcnt(5)
	v_mfma_i32_16x16x64_i8 v[46:49], v[134:137], v[186:189], v[46:49]
	v_mfma_i32_16x16x64_i8 v[42:45], v[142:145], v[186:189], v[42:45]
	s_waitcnt lgkmcnt(3)
	v_mfma_i32_16x16x64_i8 v[30:33], v[134:137], v[194:197], v[30:33]
	v_mfma_i32_16x16x64_i8 v[26:29], v[142:145], v[194:197], v[26:29]
	s_waitcnt lgkmcnt(1)
	v_mfma_i32_16x16x64_i8 v[14:17], v[134:137], v[202:205], v[14:17]
	v_mfma_i32_16x16x64_i8 v[10:13], v[142:145], v[202:205], v[10:13]
	v_mfma_i32_16x16x64_i8 v[62:65], v[138:141], v[182:185], v[62:65]
	v_mfma_i32_16x16x64_i8 v[58:61], v[146:149], v[182:185], v[58:61]
	v_mfma_i32_16x16x64_i8 v[46:49], v[138:141], v[190:193], v[46:49]
	v_mfma_i32_16x16x64_i8 v[42:45], v[146:149], v[190:193], v[42:45]
	v_mfma_i32_16x16x64_i8 v[30:33], v[138:141], v[198:201], v[30:33]
	v_mfma_i32_16x16x64_i8 v[26:29], v[146:149], v[198:201], v[26:29]
	s_waitcnt lgkmcnt(0)
	v_mfma_i32_16x16x64_i8 v[14:17], v[138:141], v[206:209], v[14:17]
	v_mfma_i32_16x16x64_i8 v[10:13], v[146:149], v[206:209], v[10:13]
	s_setprio 0
	s_setprio 1
	v_mfma_i32_16x16x64_i8 v[54:57], v[150:153], v[178:181], v[54:57]
	v_mfma_i32_16x16x64_i8 v[50:53], v[170:173], v[178:181], v[50:53]
	v_mfma_i32_16x16x64_i8 v[38:41], v[150:153], v[186:189], v[38:41]
	v_mfma_i32_16x16x64_i8 v[34:37], v[170:173], v[186:189], v[34:37]
	v_mfma_i32_16x16x64_i8 v[22:25], v[150:153], v[194:197], v[22:25]
	v_mfma_i32_16x16x64_i8 v[18:21], v[170:173], v[194:197], v[18:21]
	v_mfma_i32_16x16x64_i8 v[6:9], v[150:153], v[202:205], v[6:9]
	v_mfma_i32_16x16x64_i8 v[2:5], v[170:173], v[202:205], v[2:5]
	v_mfma_i32_16x16x64_i8 v[54:57], v[166:169], v[182:185], v[54:57]
	v_mfma_i32_16x16x64_i8 v[50:53], v[174:177], v[182:185], v[50:53]
	v_mfma_i32_16x16x64_i8 v[38:41], v[166:169], v[190:193], v[38:41]
	v_mfma_i32_16x16x64_i8 v[34:37], v[174:177], v[190:193], v[34:37]
	v_mfma_i32_16x16x64_i8 v[22:25], v[166:169], v[198:201], v[22:25]
	v_mfma_i32_16x16x64_i8 v[18:21], v[174:177], v[198:201], v[18:21]
	v_mfma_i32_16x16x64_i8 v[6:9], v[166:169], v[206:209], v[6:9]
	v_mfma_i32_16x16x64_i8 v[2:5], v[174:177], v[206:209], v[2:5]
	s_setprio 0
	s_add_i32 s80, s80, 2
	s_addk_i32 s78, 0x100
	s_addk_i32 s79, 0x100
	s_cmp_gt_u32 s80, 13
	s_barrier
	s_cbranch_scc0 .LBB0_289
	s_and_b64 vcc, exec, s[16:17]
	s_cbranch_vccz .LBB0_292
	s_barrier

.LBB0_816:
	ds_read_b128 v[134:137], v218
	ds_read_b128 v[158:161], v218 offset:1024
	ds_read_b128 v[162:165], v218 offset:2048
	ds_read_b128 v[166:169], v218 offset:3072
	ds_read_b128 v[170:173], v219
	ds_read_b128 v[174:177], v219 offset:1024
	ds_read_b128 v[178:181], v219 offset:2048
	ds_read_b128 v[182:185], v219 offset:3072
	s_add_i32 s47, s66, 0xfff80080
	s_cmp_eq_u32 s76, 28
	s_cselect_b32 s79, s64, s47
	s_cselect_b32 s78, s65, s67
	s_or_b32 s77, s79, 0x80
	s_mov_b32 s47, s31
	s_mov_b32 m0, s53
	ds_read_b128 v[186:189], v156
	ds_read_b128 v[190:193], v156 offset:1024
	ds_read_b128 v[194:197], v156 offset:2048
	ds_read_b128 v[198:201], v156 offset:3072
	ds_read_b128 v[202:205], v156 offset:4096
	ds_read_b128 v[206:209], v156 offset:5120
	ds_read_b128 v[210:213], v156 offset:6144
	ds_read_b128 v[214:217], v156 offset:7168
	buffer_load_dwordx4 v131, s[44:47], s66 offen lds
	s_mov_b32 m0, s56
	s_nop 0
	buffer_load_dwordx4 v150, s[44:47], s66 offen lds
	s_waitcnt vmcnt(8)
	s_waitcnt lgkmcnt(0)
	s_barrier
	s_setprio 1
	s_waitcnt lgkmcnt(7)
	v_mfma_f32_16x16x32_bf16 v[126:129], v[134:137], v[186:189], v[126:129]
	v_mfma_f32_16x16x32_bf16 v[122:125], v[162:165], v[186:189], v[122:125]
	s_waitcnt lgkmcnt(5)
	v_mfma_f32_16x16x32_bf16 v[118:121], v[134:137], v[194:197], v[118:121]
	v_mfma_f32_16x16x32_bf16 v[110:113], v[162:165], v[194:197], v[110:113]
	s_waitcnt lgkmcnt(3)
	v_mfma_f32_16x16x32_bf16 v[102:105], v[134:137], v[202:205], v[102:105]
	v_mfma_f32_16x16x32_bf16 v[94:97], v[162:165], v[202:205], v[94:97]
	s_waitcnt lgkmcnt(1)
	v_mfma_f32_16x16x32_bf16 v[86:89], v[134:137], v[210:213], v[86:89]
	v_mfma_f32_16x16x32_bf16 v[78:81], v[162:165], v[210:213], v[78:81]
	v_mfma_f32_16x16x32_bf16 v[126:129], v[158:161], v[190:193], v[126:129]
	v_mfma_f32_16x16x32_bf16 v[122:125], v[166:169], v[190:193], v[122:125]
	v_mfma_f32_16x16x32_bf16 v[118:121], v[158:161], v[198:201], v[118:121]
	v_mfma_f32_16x16x32_bf16 v[110:113], v[166:169], v[198:201], v[110:113]
	v_mfma_f32_16x16x32_bf16 v[102:105], v[158:161], v[206:209], v[102:105]
	v_mfma_f32_16x16x32_bf16 v[94:97], v[166:169], v[206:209], v[94:97]
	s_waitcnt lgkmcnt(0)
	v_mfma_f32_16x16x32_bf16 v[86:89], v[158:161], v[214:217], v[86:89]
	v_mfma_f32_16x16x32_bf16 v[78:81], v[166:169], v[214:217], v[78:81]
	s_setprio 0
	s_setprio 1
	v_mfma_f32_16x16x32_bf16 v[114:117], v[170:173], v[186:189], v[114:117]
	v_mfma_f32_16x16x32_bf16 v[106:109], v[178:181], v[186:189], v[106:109]
	v_mfma_f32_16x16x32_bf16 v[98:101], v[170:173], v[194:197], v[98:101]
	v_mfma_f32_16x16x32_bf16 v[90:93], v[178:181], v[194:197], v[90:93]
	v_mfma_f32_16x16x32_bf16 v[82:85], v[170:173], v[202:205], v[82:85]
	v_mfma_f32_16x16x32_bf16 v[74:77], v[178:181], v[202:205], v[74:77]
	v_mfma_f32_16x16x32_bf16 v[70:73], v[170:173], v[210:213], v[70:73]
	v_mfma_f32_16x16x32_bf16 v[66:69], v[178:181], v[210:213], v[66:69]
	v_mfma_f32_16x16x32_bf16 v[114:117], v[174:177], v[190:193], v[114:117]
	v_mfma_f32_16x16x32_bf16 v[106:109], v[182:185], v[190:193], v[106:109]
	v_mfma_f32_16x16x32_bf16 v[98:101], v[174:177], v[198:201], v[98:101]
	v_mfma_f32_16x16x32_bf16 v[90:93], v[182:185], v[198:201], v[90:93]
	v_mfma_f32_16x16x32_bf16 v[82:85], v[174:177], v[206:209], v[82:85]
	v_mfma_f32_16x16x32_bf16 v[74:77], v[182:185], v[206:209], v[74:77]
	v_mfma_f32_16x16x32_bf16 v[70:73], v[174:177], v[214:217], v[70:73]
	v_mfma_f32_16x16x32_bf16 v[66:69], v[182:185], v[214:217], v[66:69]
	s_setprio 0
	s_barrier
	s_mov_b32 m0, s18
	s_mov_b32 s51, s31
	ds_read_b128 v[186:189], v156 offset:16384
	ds_read_b128 v[190:193], v156 offset:17408
	ds_read_b128 v[194:197], v156 offset:18432
	ds_read_b128 v[198:201], v156 offset:19456
	ds_read_b128 v[202:205], v156 offset:20480
	ds_read_b128 v[206:209], v156 offset:21504
	ds_read_b128 v[210:213], v156 offset:22528
	ds_read_b128 v[214:217], v156 offset:23552
	buffer_load_dwordx4 v149, s[48:51], s78 offen lds
	s_mov_b32 m0, s19
	s_add_i32 s80, s78, 0x80000
	buffer_load_dwordx4 v151, s[48:51], s78 offen lds
	s_mov_b32 m0, s22
	s_nop 0
	buffer_load_dwordx4 v149, s[48:51], s80 offen lds
	s_mov_b32 m0, s23
	s_nop 0
	buffer_load_dwordx4 v151, s[48:51], s80 offen lds
	s_mov_b32 m0, s17
	s_nop 0
	buffer_load_dwordx4 v131, s[44:47], s79 offen lds
	s_mov_b32 m0, s28
	s_nop 0
	buffer_load_dwordx4 v150, s[44:47], s79 offen lds
	s_waitcnt vmcnt(8)
	s_waitcnt lgkmcnt(0)
	s_barrier
	s_setprio 1
	s_waitcnt lgkmcnt(7)
	v_mfma_f32_16x16x32_bf16 v[62:65], v[134:137], v[186:189], v[62:65]
	v_mfma_f32_16x16x32_bf16 v[58:61], v[162:165], v[186:189], v[58:61]
	s_waitcnt lgkmcnt(5)
	v_mfma_f32_16x16x32_bf16 v[54:57], v[134:137], v[194:197], v[54:57]
	v_mfma_f32_16x16x32_bf16 v[46:49], v[162:165], v[194:197], v[46:49]
	s_waitcnt lgkmcnt(3)
	v_mfma_f32_16x16x32_bf16 v[38:41], v[134:137], v[202:205], v[38:41]
	v_mfma_f32_16x16x32_bf16 v[30:33], v[162:165], v[202:205], v[30:33]
	s_waitcnt lgkmcnt(1)
	v_mfma_f32_16x16x32_bf16 v[22:25], v[134:137], v[210:213], v[22:25]
	v_mfma_f32_16x16x32_bf16 v[14:17], v[162:165], v[210:213], v[14:17]
	v_mfma_f32_16x16x32_bf16 v[62:65], v[158:161], v[190:193], v[62:65]
	v_mfma_f32_16x16x32_bf16 v[58:61], v[166:169], v[190:193], v[58:61]
	v_mfma_f32_16x16x32_bf16 v[54:57], v[158:161], v[198:201], v[54:57]
	v_mfma_f32_16x16x32_bf16 v[46:49], v[166:169], v[198:201], v[46:49]
	v_mfma_f32_16x16x32_bf16 v[38:41], v[158:161], v[206:209], v[38:41]
	v_mfma_f32_16x16x32_bf16 v[30:33], v[166:169], v[206:209], v[30:33]
	s_waitcnt lgkmcnt(0)
	v_mfma_f32_16x16x32_bf16 v[22:25], v[158:161], v[214:217], v[22:25]
	v_mfma_f32_16x16x32_bf16 v[14:17], v[166:169], v[214:217], v[14:17]
	s_setprio 0
	s_setprio 1
	v_mfma_f32_16x16x32_bf16 v[50:53], v[170:173], v[186:189], v[50:53]
	v_mfma_f32_16x16x32_bf16 v[42:45], v[178:181], v[186:189], v[42:45]
	v_mfma_f32_16x16x32_bf16 v[34:37], v[170:173], v[194:197], v[34:37]
	v_mfma_f32_16x16x32_bf16 v[26:29], v[178:181], v[194:197], v[26:29]
	v_mfma_f32_16x16x32_bf16 v[18:21], v[170:173], v[202:205], v[18:21]
	v_mfma_f32_16x16x32_bf16 v[10:13], v[178:181], v[202:205], v[10:13]
	v_mfma_f32_16x16x32_bf16 v[6:9], v[170:173], v[210:213], v[6:9]
	v_mfma_f32_16x16x32_bf16 v[2:5], v[178:181], v[210:213], v[2:5]
	v_mfma_f32_16x16x32_bf16 v[50:53], v[174:177], v[190:193], v[50:53]
	v_mfma_f32_16x16x32_bf16 v[42:45], v[182:185], v[190:193], v[42:45]
	v_mfma_f32_16x16x32_bf16 v[34:37], v[174:177], v[198:201], v[34:37]
	v_mfma_f32_16x16x32_bf16 v[26:29], v[182:185], v[198:201], v[26:29]
	v_mfma_f32_16x16x32_bf16 v[18:21], v[174:177], v[206:209], v[18:21]
	v_mfma_f32_16x16x32_bf16 v[10:13], v[182:185], v[206:209], v[10:13]
	v_mfma_f32_16x16x32_bf16 v[6:9], v[174:177], v[214:217], v[6:9]
	v_mfma_f32_16x16x32_bf16 v[2:5], v[182:185], v[214:217], v[2:5]
	s_setprio 0
	s_barrier
	ds_read_b128 v[134:137], v220
	ds_read_b128 v[158:161], v220 offset:1024
	ds_read_b128 v[162:165], v220 offset:2048
	ds_read_b128 v[166:169], v220 offset:3072
	ds_read_b128 v[170:173], v221
	ds_read_b128 v[174:177], v221 offset:1024
	ds_read_b128 v[178:181], v221 offset:2048
	ds_read_b128 v[182:185], v221 offset:3072
	s_add_i32 s79, s79, 0x80000
	s_mov_b32 m0, s29
	ds_read_b128 v[186:189], v156 offset:32768
	ds_read_b128 v[190:193], v156 offset:33792
	ds_read_b128 v[194:197], v156 offset:34816
	ds_read_b128 v[198:201], v156 offset:35840
	ds_read_b128 v[202:205], v156 offset:36864
	ds_read_b128 v[206:209], v156 offset:37888
	ds_read_b128 v[210:213], v156 offset:38912
	ds_read_b128 v[214:217], v156 offset:39936
	buffer_load_dwordx4 v131, s[44:47], s79 offen lds
	s_mov_b32 m0, s34
	s_nop 0
	buffer_load_dwordx4 v150, s[44:47], s79 offen lds
	s_waitcnt vmcnt(8)
	s_waitcnt lgkmcnt(0)
	s_barrier
	s_setprio 1
	s_waitcnt lgkmcnt(7)
	v_mfma_f32_16x16x32_bf16 v[126:129], v[134:137], v[186:189], v[126:129]
	v_mfma_f32_16x16x32_bf16 v[122:125], v[162:165], v[186:189], v[122:125]
	s_waitcnt lgkmcnt(5)
	v_mfma_f32_16x16x32_bf16 v[118:121], v[134:137], v[194:197], v[118:121]
	v_mfma_f32_16x16x32_bf16 v[110:113], v[162:165], v[194:197], v[110:113]
	s_waitcnt lgkmcnt(3)
	v_mfma_f32_16x16x32_bf16 v[102:105], v[134:137], v[202:205], v[102:105]
	v_mfma_f32_16x16x32_bf16 v[94:97], v[162:165], v[202:205], v[94:97]
	s_waitcnt lgkmcnt(1)
	v_mfma_f32_16x16x32_bf16 v[86:89], v[134:137], v[210:213], v[86:89]
	v_mfma_f32_16x16x32_bf16 v[78:81], v[162:165], v[210:213], v[78:81]
	v_mfma_f32_16x16x32_bf16 v[126:129], v[158:161], v[190:193], v[126:129]
	v_mfma_f32_16x16x32_bf16 v[122:125], v[166:169], v[190:193], v[122:125]
	v_mfma_f32_16x16x32_bf16 v[118:121], v[158:161], v[198:201], v[118:121]
	v_mfma_f32_16x16x32_bf16 v[110:113], v[166:169], v[198:201], v[110:113]
	v_mfma_f32_16x16x32_bf16 v[102:105], v[158:161], v[206:209], v[102:105]
	v_mfma_f32_16x16x32_bf16 v[94:97], v[166:169], v[206:209], v[94:97]
	s_waitcnt lgkmcnt(0)
	v_mfma_f32_16x16x32_bf16 v[86:89], v[158:161], v[214:217], v[86:89]
	v_mfma_f32_16x16x32_bf16 v[78:81], v[166:169], v[214:217], v[78:81]
	s_setprio 0
	s_setprio 1
	v_mfma_f32_16x16x32_bf16 v[114:117], v[170:173], v[186:189], v[114:117]
	v_mfma_f32_16x16x32_bf16 v[106:109], v[178:181], v[186:189], v[106:109]
	v_mfma_f32_16x16x32_bf16 v[98:101], v[170:173], v[194:197], v[98:101]
	v_mfma_f32_16x16x32_bf16 v[90:93], v[178:181], v[194:197], v[90:93]
	v_mfma_f32_16x16x32_bf16 v[82:85], v[170:173], v[202:205], v[82:85]
	v_mfma_f32_16x16x32_bf16 v[74:77], v[178:181], v[202:205], v[74:77]
	v_mfma_f32_16x16x32_bf16 v[70:73], v[170:173], v[210:213], v[70:73]
	v_mfma_f32_16x16x32_bf16 v[66:69], v[178:181], v[210:213], v[66:69]
	v_mfma_f32_16x16x32_bf16 v[114:117], v[174:177], v[190:193], v[114:117]
	v_mfma_f32_16x16x32_bf16 v[106:109], v[182:185], v[190:193], v[106:109]
	v_mfma_f32_16x16x32_bf16 v[98:101], v[174:177], v[198:201], v[98:101]
	v_mfma_f32_16x16x32_bf16 v[90:93], v[182:185], v[198:201], v[90:93]
	v_mfma_f32_16x16x32_bf16 v[82:85], v[174:177], v[206:209], v[82:85]
	v_mfma_f32_16x16x32_bf16 v[74:77], v[182:185], v[206:209], v[74:77]
	v_mfma_f32_16x16x32_bf16 v[70:73], v[174:177], v[214:217], v[70:73]
	v_mfma_f32_16x16x32_bf16 v[66:69], v[182:185], v[214:217], v[66:69]
	s_setprio 0
	s_barrier
	s_mov_b32 m0, s35
	s_or_b32 s79, s78, 0x80
	ds_read_b128 v[186:189], v156 offset:49152
	ds_read_b128 v[190:193], v156 offset:50176
	ds_read_b128 v[194:197], v156 offset:51200
	ds_read_b128 v[198:201], v156 offset:52224
	ds_read_b128 v[202:205], v156 offset:53248
	ds_read_b128 v[206:209], v156 offset:54272
	ds_read_b128 v[210:213], v156 offset:55296
	ds_read_b128 v[214:217], v156 offset:56320
	buffer_load_dwordx4 v149, s[48:51], s79 offen lds
	s_mov_b32 m0, s36
	s_add_i32 s78, s78, 0x80080
	buffer_load_dwordx4 v151, s[48:51], s79 offen lds
	s_mov_b32 m0, s41
	s_nop 0
	buffer_load_dwordx4 v149, s[48:51], s78 offen lds
	s_mov_b32 m0, s52
	s_nop 0
	buffer_load_dwordx4 v151, s[48:51], s78 offen lds
	s_mov_b32 m0, s37
	s_nop 0
	buffer_load_dwordx4 v131, s[44:47], s77 offen lds
	s_mov_b32 m0, s40
	s_nop 0
	buffer_load_dwordx4 v150, s[44:47], s77 offen lds
	s_waitcnt vmcnt(8)
	s_waitcnt lgkmcnt(0)
	s_barrier
	s_setprio 1
	s_waitcnt lgkmcnt(7)
	v_mfma_f32_16x16x32_bf16 v[62:65], v[134:137], v[186:189], v[62:65]
	v_mfma_f32_16x16x32_bf16 v[58:61], v[162:165], v[186:189], v[58:61]
	s_waitcnt lgkmcnt(5)
	v_mfma_f32_16x16x32_bf16 v[54:57], v[134:137], v[194:197], v[54:57]
	v_mfma_f32_16x16x32_bf16 v[46:49], v[162:165], v[194:197], v[46:49]
	s_waitcnt lgkmcnt(3)
	v_mfma_f32_16x16x32_bf16 v[38:41], v[134:137], v[202:205], v[38:41]
	v_mfma_f32_16x16x32_bf16 v[30:33], v[162:165], v[202:205], v[30:33]
	s_waitcnt lgkmcnt(1)
	v_mfma_f32_16x16x32_bf16 v[22:25], v[134:137], v[210:213], v[22:25]
	v_mfma_f32_16x16x32_bf16 v[14:17], v[162:165], v[210:213], v[14:17]
	v_mfma_f32_16x16x32_bf16 v[62:65], v[158:161], v[190:193], v[62:65]
	v_mfma_f32_16x16x32_bf16 v[58:61], v[166:169], v[190:193], v[58:61]
	v_mfma_f32_16x16x32_bf16 v[54:57], v[158:161], v[198:201], v[54:57]
	v_mfma_f32_16x16x32_bf16 v[46:49], v[166:169], v[198:201], v[46:49]
	v_mfma_f32_16x16x32_bf16 v[38:41], v[158:161], v[206:209], v[38:41]
	v_mfma_f32_16x16x32_bf16 v[30:33], v[166:169], v[206:209], v[30:33]
	s_waitcnt lgkmcnt(0)
	v_mfma_f32_16x16x32_bf16 v[22:25], v[158:161], v[214:217], v[22:25]
	v_mfma_f32_16x16x32_bf16 v[14:17], v[166:169], v[214:217], v[14:17]
	s_setprio 0
	s_setprio 1
	v_mfma_f32_16x16x32_bf16 v[50:53], v[170:173], v[186:189], v[50:53]
	v_mfma_f32_16x16x32_bf16 v[42:45], v[178:181], v[186:189], v[42:45]
	v_mfma_f32_16x16x32_bf16 v[34:37], v[170:173], v[194:197], v[34:37]
	v_mfma_f32_16x16x32_bf16 v[26:29], v[178:181], v[194:197], v[26:29]
	v_mfma_f32_16x16x32_bf16 v[18:21], v[170:173], v[202:205], v[18:21]
	v_mfma_f32_16x16x32_bf16 v[10:13], v[178:181], v[202:205], v[10:13]
	v_mfma_f32_16x16x32_bf16 v[6:9], v[170:173], v[210:213], v[6:9]
	v_mfma_f32_16x16x32_bf16 v[2:5], v[178:181], v[210:213], v[2:5]
	v_mfma_f32_16x16x32_bf16 v[50:53], v[174:177], v[190:193], v[50:53]
	v_mfma_f32_16x16x32_bf16 v[42:45], v[182:185], v[190:193], v[42:45]
	v_mfma_f32_16x16x32_bf16 v[34:37], v[174:177], v[198:201], v[34:37]
	v_mfma_f32_16x16x32_bf16 v[26:29], v[182:185], v[198:201], v[26:29]
	v_mfma_f32_16x16x32_bf16 v[18:21], v[174:177], v[206:209], v[18:21]
	v_mfma_f32_16x16x32_bf16 v[10:13], v[182:185], v[206:209], v[10:13]
	v_mfma_f32_16x16x32_bf16 v[6:9], v[174:177], v[214:217], v[6:9]
	v_mfma_f32_16x16x32_bf16 v[2:5], v[182:185], v[214:217], v[2:5]
	s_setprio 0
	s_add_i32 s76, s76, 2
	s_addk_i32 s66, 0x100
	s_addk_i32 s67, 0x100
	s_cmp_gt_u32 s76, 29
	s_barrier
	s_cbranch_scc0 .LBB0_816
	s_and_b64 vcc, exec, s[10:11]
	s_cbranch_vccz .LBB0_819
	s_barrier

.LBB0_844:
	ds_read_b128 v[122:125], v218
	ds_read_b128 v[126:129], v218 offset:1024
	ds_read_b128 v[130:133], v218 offset:2048
	ds_read_b128 v[134:137], v218 offset:3072
	ds_read_b128 v[162:165], v219
	ds_read_b128 v[166:169], v219 offset:1024
	ds_read_b128 v[170:173], v219 offset:2048
	ds_read_b128 v[174:177], v219 offset:3072
	s_add_i32 s55, s76, 0xfffc0080
	s_cmp_eq_u32 s78, 12
	s_cselect_b32 s82, s66, s55
	s_cselect_b32 s80, s67, s77
	s_or_b32 s79, s82, 0x80
	s_mov_b32 m0, s59
	ds_read_b128 v[178:181], v160
	ds_read_b128 v[182:185], v160 offset:1024
	ds_read_b128 v[186:189], v160 offset:2048
	ds_read_b128 v[190:193], v160 offset:3072
	ds_read_b128 v[194:197], v160 offset:4096
	ds_read_b128 v[198:201], v160 offset:5120
	ds_read_b128 v[202:205], v160 offset:6144
	ds_read_b128 v[206:209], v160 offset:7168
	buffer_load_dwordx4 v153, s[28:31], s76 offen lds
	s_mov_b32 m0, s60
	s_nop 0
	buffer_load_dwordx4 v155, s[28:31], s76 offen lds
	s_waitcnt vmcnt(8)
	s_waitcnt lgkmcnt(0)
	s_barrier
	s_setprio 1
	s_waitcnt lgkmcnt(0)
	v_mfma_i32_16x16x64_i8 v[142:145], v[122:125], v[178:181], v[142:145]
	v_mfma_i32_16x16x64_i8 v[138:141], v[130:133], v[178:181], v[138:141]
	v_mfma_i32_16x16x64_i8 v[110:113], v[122:125], v[186:189], v[110:113]
	v_mfma_i32_16x16x64_i8 v[106:109], v[130:133], v[186:189], v[106:109]
	v_mfma_i32_16x16x64_i8 v[94:97], v[122:125], v[194:197], v[94:97]
	v_mfma_i32_16x16x64_i8 v[90:93], v[130:133], v[194:197], v[90:93]
	v_mfma_i32_16x16x64_i8 v[78:81], v[122:125], v[202:205], v[78:81]
	v_mfma_i32_16x16x64_i8 v[74:77], v[130:133], v[202:205], v[74:77]
	v_mfma_i32_16x16x64_i8 v[142:145], v[126:129], v[182:185], v[142:145]
	v_mfma_i32_16x16x64_i8 v[138:141], v[134:137], v[182:185], v[138:141]
	v_mfma_i32_16x16x64_i8 v[110:113], v[126:129], v[190:193], v[110:113]
	v_mfma_i32_16x16x64_i8 v[106:109], v[134:137], v[190:193], v[106:109]
	v_mfma_i32_16x16x64_i8 v[94:97], v[126:129], v[198:201], v[94:97]
	v_mfma_i32_16x16x64_i8 v[90:93], v[134:137], v[198:201], v[90:93]
	v_mfma_i32_16x16x64_i8 v[78:81], v[126:129], v[206:209], v[78:81]
	v_mfma_i32_16x16x64_i8 v[74:77], v[134:137], v[206:209], v[74:77]
	s_setprio 0
	s_setprio 1
	v_mfma_i32_16x16x64_i8 v[118:121], v[162:165], v[178:181], v[118:121]
	v_mfma_i32_16x16x64_i8 v[114:117], v[170:173], v[178:181], v[114:117]
	v_mfma_i32_16x16x64_i8 v[102:105], v[162:165], v[186:189], v[102:105]
	v_mfma_i32_16x16x64_i8 v[98:101], v[170:173], v[186:189], v[98:101]
	v_mfma_i32_16x16x64_i8 v[86:89], v[162:165], v[194:197], v[86:89]
	v_mfma_i32_16x16x64_i8 v[82:85], v[170:173], v[194:197], v[82:85]
	v_mfma_i32_16x16x64_i8 v[70:73], v[162:165], v[202:205], v[70:73]
	v_mfma_i32_16x16x64_i8 v[66:69], v[170:173], v[202:205], v[66:69]
	v_mfma_i32_16x16x64_i8 v[118:121], v[166:169], v[182:185], v[118:121]
	v_mfma_i32_16x16x64_i8 v[114:117], v[174:177], v[182:185], v[114:117]
	v_mfma_i32_16x16x64_i8 v[102:105], v[166:169], v[190:193], v[102:105]
	v_mfma_i32_16x16x64_i8 v[98:101], v[174:177], v[190:193], v[98:101]
	v_mfma_i32_16x16x64_i8 v[86:89], v[166:169], v[198:201], v[86:89]
	v_mfma_i32_16x16x64_i8 v[82:85], v[174:177], v[198:201], v[82:85]
	v_mfma_i32_16x16x64_i8 v[70:73], v[166:169], v[206:209], v[70:73]
	v_mfma_i32_16x16x64_i8 v[66:69], v[174:177], v[206:209], v[66:69]
	s_setprio 0
	s_barrier
	s_mov_b32 m0, s34
	s_mov_b32 s55, s31
	ds_read_b128 v[178:181], v160 offset:16384
	ds_read_b128 v[182:185], v160 offset:17408
	ds_read_b128 v[186:189], v160 offset:18432
	ds_read_b128 v[190:193], v160 offset:19456
	ds_read_b128 v[194:197], v160 offset:20480
	ds_read_b128 v[198:201], v160 offset:21504
	ds_read_b128 v[202:205], v160 offset:22528
	ds_read_b128 v[206:209], v160 offset:23552
	buffer_load_dwordx4 v154, s[52:55], s80 offen lds
	s_mov_b32 m0, s35
	s_add_i32 s83, s80, 0x40000
	buffer_load_dwordx4 v156, s[52:55], s80 offen lds
	s_mov_b32 m0, s36
	s_nop 0
	buffer_load_dwordx4 v154, s[52:55], s83 offen lds
	s_mov_b32 m0, s37
	s_nop 0
	buffer_load_dwordx4 v156, s[52:55], s83 offen lds
	s_mov_b32 m0, s23
	s_nop 0
	buffer_load_dwordx4 v153, s[28:31], s82 offen lds
	s_mov_b32 m0, s40
	s_nop 0
	buffer_load_dwordx4 v155, s[28:31], s82 offen lds
	s_waitcnt vmcnt(8)
	s_waitcnt lgkmcnt(0)
	s_barrier
	s_setprio 1
	s_waitcnt lgkmcnt(0)
	v_mfma_i32_16x16x64_i8 v[62:65], v[122:125], v[178:181], v[62:65]
	v_mfma_i32_16x16x64_i8 v[58:61], v[130:133], v[178:181], v[58:61]
	v_mfma_i32_16x16x64_i8 v[46:49], v[122:125], v[186:189], v[46:49]
	v_mfma_i32_16x16x64_i8 v[42:45], v[130:133], v[186:189], v[42:45]
	v_mfma_i32_16x16x64_i8 v[30:33], v[122:125], v[194:197], v[30:33]
	v_mfma_i32_16x16x64_i8 v[26:29], v[130:133], v[194:197], v[26:29]
	v_mfma_i32_16x16x64_i8 v[14:17], v[122:125], v[202:205], v[14:17]
	v_mfma_i32_16x16x64_i8 v[10:13], v[130:133], v[202:205], v[10:13]
	v_mfma_i32_16x16x64_i8 v[62:65], v[126:129], v[182:185], v[62:65]
	v_mfma_i32_16x16x64_i8 v[58:61], v[134:137], v[182:185], v[58:61]
	v_mfma_i32_16x16x64_i8 v[46:49], v[126:129], v[190:193], v[46:49]
	v_mfma_i32_16x16x64_i8 v[42:45], v[134:137], v[190:193], v[42:45]
	v_mfma_i32_16x16x64_i8 v[30:33], v[126:129], v[198:201], v[30:33]
	v_mfma_i32_16x16x64_i8 v[26:29], v[134:137], v[198:201], v[26:29]
	v_mfma_i32_16x16x64_i8 v[14:17], v[126:129], v[206:209], v[14:17]
	v_mfma_i32_16x16x64_i8 v[10:13], v[134:137], v[206:209], v[10:13]
	s_setprio 0
	s_setprio 1
	v_mfma_i32_16x16x64_i8 v[54:57], v[162:165], v[178:181], v[54:57]
	v_mfma_i32_16x16x64_i8 v[50:53], v[170:173], v[178:181], v[50:53]
	v_mfma_i32_16x16x64_i8 v[38:41], v[162:165], v[186:189], v[38:41]
	v_mfma_i32_16x16x64_i8 v[34:37], v[170:173], v[186:189], v[34:37]
	v_mfma_i32_16x16x64_i8 v[22:25], v[162:165], v[194:197], v[22:25]
	v_mfma_i32_16x16x64_i8 v[18:21], v[170:173], v[194:197], v[18:21]
	v_mfma_i32_16x16x64_i8 v[6:9], v[162:165], v[202:205], v[6:9]
	v_mfma_i32_16x16x64_i8 v[2:5], v[170:173], v[202:205], v[2:5]
	v_mfma_i32_16x16x64_i8 v[54:57], v[166:169], v[182:185], v[54:57]
	v_mfma_i32_16x16x64_i8 v[50:53], v[174:177], v[182:185], v[50:53]
	v_mfma_i32_16x16x64_i8 v[38:41], v[166:169], v[190:193], v[38:41]
	v_mfma_i32_16x16x64_i8 v[34:37], v[174:177], v[190:193], v[34:37]
	v_mfma_i32_16x16x64_i8 v[22:25], v[166:169], v[198:201], v[22:25]
	v_mfma_i32_16x16x64_i8 v[18:21], v[174:177], v[198:201], v[18:21]
	v_mfma_i32_16x16x64_i8 v[6:9], v[166:169], v[206:209], v[6:9]
	v_mfma_i32_16x16x64_i8 v[2:5], v[174:177], v[206:209], v[2:5]
	s_setprio 0
	s_barrier
	ds_read_b128 v[122:125], v220
	ds_read_b128 v[126:129], v220 offset:1024
	ds_read_b128 v[130:133], v220 offset:2048
	ds_read_b128 v[134:137], v220 offset:3072
	ds_read_b128 v[162:165], v221
	ds_read_b128 v[166:169], v221 offset:1024
	ds_read_b128 v[170:173], v221 offset:2048
	ds_read_b128 v[174:177], v221 offset:3072
	s_add_i32 s82, s82, 0x40000
	s_mov_b32 m0, s41
	ds_read_b128 v[178:181], v160 offset:32768
	ds_read_b128 v[182:185], v160 offset:33792
	ds_read_b128 v[186:189], v160 offset:34816
	ds_read_b128 v[190:193], v160 offset:35840
	ds_read_b128 v[194:197], v160 offset:36864
	ds_read_b128 v[198:201], v160 offset:37888
	ds_read_b128 v[202:205], v160 offset:38912
	ds_read_b128 v[206:209], v160 offset:39936
	buffer_load_dwordx4 v153, s[28:31], s82 offen lds
	s_mov_b32 m0, s43
	s_nop 0
	buffer_load_dwordx4 v155, s[28:31], s82 offen lds
	s_waitcnt vmcnt(8)
	s_waitcnt lgkmcnt(0)
	s_barrier
	s_setprio 1
	s_waitcnt lgkmcnt(0)
	v_mfma_i32_16x16x64_i8 v[142:145], v[122:125], v[178:181], v[142:145]
	v_mfma_i32_16x16x64_i8 v[138:141], v[130:133], v[178:181], v[138:141]
	v_mfma_i32_16x16x64_i8 v[110:113], v[122:125], v[186:189], v[110:113]
	v_mfma_i32_16x16x64_i8 v[106:109], v[130:133], v[186:189], v[106:109]
	v_mfma_i32_16x16x64_i8 v[94:97], v[122:125], v[194:197], v[94:97]
	v_mfma_i32_16x16x64_i8 v[90:93], v[130:133], v[194:197], v[90:93]
	v_mfma_i32_16x16x64_i8 v[78:81], v[122:125], v[202:205], v[78:81]
	v_mfma_i32_16x16x64_i8 v[74:77], v[130:133], v[202:205], v[74:77]
	v_mfma_i32_16x16x64_i8 v[142:145], v[126:129], v[182:185], v[142:145]
	v_mfma_i32_16x16x64_i8 v[138:141], v[134:137], v[182:185], v[138:141]
	v_mfma_i32_16x16x64_i8 v[110:113], v[126:129], v[190:193], v[110:113]
	v_mfma_i32_16x16x64_i8 v[106:109], v[134:137], v[190:193], v[106:109]
	v_mfma_i32_16x16x64_i8 v[94:97], v[126:129], v[198:201], v[94:97]
	v_mfma_i32_16x16x64_i8 v[90:93], v[134:137], v[198:201], v[90:93]
	v_mfma_i32_16x16x64_i8 v[78:81], v[126:129], v[206:209], v[78:81]
	v_mfma_i32_16x16x64_i8 v[74:77], v[134:137], v[206:209], v[74:77]
	s_setprio 0
	s_setprio 1
	v_mfma_i32_16x16x64_i8 v[118:121], v[162:165], v[178:181], v[118:121]
	v_mfma_i32_16x16x64_i8 v[114:117], v[170:173], v[178:181], v[114:117]
	v_mfma_i32_16x16x64_i8 v[102:105], v[162:165], v[186:189], v[102:105]
	v_mfma_i32_16x16x64_i8 v[98:101], v[170:173], v[186:189], v[98:101]
	v_mfma_i32_16x16x64_i8 v[86:89], v[162:165], v[194:197], v[86:89]
	v_mfma_i32_16x16x64_i8 v[82:85], v[170:173], v[194:197], v[82:85]
	v_mfma_i32_16x16x64_i8 v[70:73], v[162:165], v[202:205], v[70:73]
	v_mfma_i32_16x16x64_i8 v[66:69], v[170:173], v[202:205], v[66:69]
	v_mfma_i32_16x16x64_i8 v[118:121], v[166:169], v[182:185], v[118:121]
	v_mfma_i32_16x16x64_i8 v[114:117], v[174:177], v[182:185], v[114:117]
	v_mfma_i32_16x16x64_i8 v[102:105], v[166:169], v[190:193], v[102:105]
	v_mfma_i32_16x16x64_i8 v[98:101], v[174:177], v[190:193], v[98:101]
	v_mfma_i32_16x16x64_i8 v[86:89], v[166:169], v[198:201], v[86:89]
	v_mfma_i32_16x16x64_i8 v[82:85], v[174:177], v[198:201], v[82:85]
	v_mfma_i32_16x16x64_i8 v[70:73], v[166:169], v[206:209], v[70:73]
	v_mfma_i32_16x16x64_i8 v[66:69], v[174:177], v[206:209], v[66:69]
	s_setprio 0
	s_barrier
	s_mov_b32 m0, s44
	s_or_b32 s82, s80, 0x80
	ds_read_b128 v[178:181], v160 offset:49152
	ds_read_b128 v[182:185], v160 offset:50176
	ds_read_b128 v[186:189], v160 offset:51200
	ds_read_b128 v[190:193], v160 offset:52224
	ds_read_b128 v[194:197], v160 offset:53248
	ds_read_b128 v[198:201], v160 offset:54272
	ds_read_b128 v[202:205], v160 offset:55296
	ds_read_b128 v[206:209], v160 offset:56320
	buffer_load_dwordx4 v154, s[52:55], s82 offen lds
	s_mov_b32 m0, s45
	s_add_i32 s80, s80, 0x40080
	buffer_load_dwordx4 v156, s[52:55], s82 offen lds
	s_mov_b32 m0, s49
	s_nop 0
	buffer_load_dwordx4 v154, s[52:55], s80 offen lds
	s_mov_b32 m0, s51
	s_nop 0
	buffer_load_dwordx4 v156, s[52:55], s80 offen lds
	s_mov_b32 m0, s47
	s_nop 0
	buffer_load_dwordx4 v153, s[28:31], s79 offen lds
	s_mov_b32 m0, s48
	s_nop 0
	buffer_load_dwordx4 v155, s[28:31], s79 offen lds
	s_waitcnt vmcnt(8)
	s_waitcnt lgkmcnt(0)
	s_barrier
	s_setprio 1
	s_waitcnt lgkmcnt(0)
	v_mfma_i32_16x16x64_i8 v[62:65], v[122:125], v[178:181], v[62:65]
	v_mfma_i32_16x16x64_i8 v[58:61], v[130:133], v[178:181], v[58:61]
	v_mfma_i32_16x16x64_i8 v[46:49], v[122:125], v[186:189], v[46:49]
	v_mfma_i32_16x16x64_i8 v[42:45], v[130:133], v[186:189], v[42:45]
	v_mfma_i32_16x16x64_i8 v[30:33], v[122:125], v[194:197], v[30:33]
	v_mfma_i32_16x16x64_i8 v[26:29], v[130:133], v[194:197], v[26:29]
	v_mfma_i32_16x16x64_i8 v[14:17], v[122:125], v[202:205], v[14:17]
	v_mfma_i32_16x16x64_i8 v[10:13], v[130:133], v[202:205], v[10:13]
	v_mfma_i32_16x16x64_i8 v[62:65], v[126:129], v[182:185], v[62:65]
	v_mfma_i32_16x16x64_i8 v[58:61], v[134:137], v[182:185], v[58:61]
	v_mfma_i32_16x16x64_i8 v[46:49], v[126:129], v[190:193], v[46:49]
	v_mfma_i32_16x16x64_i8 v[42:45], v[134:137], v[190:193], v[42:45]
	v_mfma_i32_16x16x64_i8 v[30:33], v[126:129], v[198:201], v[30:33]
	v_mfma_i32_16x16x64_i8 v[26:29], v[134:137], v[198:201], v[26:29]
	v_mfma_i32_16x16x64_i8 v[14:17], v[126:129], v[206:209], v[14:17]
	v_mfma_i32_16x16x64_i8 v[10:13], v[134:137], v[206:209], v[10:13]
	s_setprio 0
	s_setprio 1
	v_mfma_i32_16x16x64_i8 v[54:57], v[162:165], v[178:181], v[54:57]
	v_mfma_i32_16x16x64_i8 v[50:53], v[170:173], v[178:181], v[50:53]
	v_mfma_i32_16x16x64_i8 v[38:41], v[162:165], v[186:189], v[38:41]
	v_mfma_i32_16x16x64_i8 v[34:37], v[170:173], v[186:189], v[34:37]
	v_mfma_i32_16x16x64_i8 v[22:25], v[162:165], v[194:197], v[22:25]
	v_mfma_i32_16x16x64_i8 v[18:21], v[170:173], v[194:197], v[18:21]
	v_mfma_i32_16x16x64_i8 v[6:9], v[162:165], v[202:205], v[6:9]
	v_mfma_i32_16x16x64_i8 v[2:5], v[170:173], v[202:205], v[2:5]
	v_mfma_i32_16x16x64_i8 v[54:57], v[166:169], v[182:185], v[54:57]
	v_mfma_i32_16x16x64_i8 v[50:53], v[174:177], v[182:185], v[50:53]
	v_mfma_i32_16x16x64_i8 v[38:41], v[166:169], v[190:193], v[38:41]
	v_mfma_i32_16x16x64_i8 v[34:37], v[174:177], v[190:193], v[34:37]
	v_mfma_i32_16x16x64_i8 v[22:25], v[166:169], v[198:201], v[22:25]
	v_mfma_i32_16x16x64_i8 v[18:21], v[174:177], v[198:201], v[18:21]
	v_mfma_i32_16x16x64_i8 v[6:9], v[166:169], v[206:209], v[6:9]
	v_mfma_i32_16x16x64_i8 v[2:5], v[174:177], v[206:209], v[2:5]
	s_setprio 0
	s_add_i32 s78, s78, 2
	s_addk_i32 s76, 0x100
	s_addk_i32 s77, 0x100
	s_cmp_gt_u32 s78, 13
	s_barrier
	s_cbranch_scc0 .LBB0_844
	s_and_b64 vcc, exec, s[12:13]
	s_cbranch_vccz .LBB0_847
	s_barrier

.LBB0_1160:
	v_and_b32_e32 v219, 15, v210
	v_and_b32_e32 v2, 48, v210
	v_lshlrev_b32_e32 v3, 2, v210
	s_and_b32 s55, s10, 3
	s_lshl_b32 s19, s83, 13
	v_lshl_or_b32 v2, v219, 6, v2
	v_and_b32_e32 v3, 32, v3
	v_bitop3_b32 v4, v2, s19, v3 bitop3:0xde
	s_lshl_b32 s19, s55, 12
	v_bitop3_b32 v3, s19, v2, v3 bitop3:0xf6
	s_add_i32 s19, s7, 0x18000
	s_or_b32 s53, s6, 0x80
	s_mov_b32 m0, s19
	s_add_i32 s52, s7, 0x1a000
	s_waitcnt vmcnt(2)
	s_barrier
	buffer_load_dwordx4 v131, s[56:59], s53 offen lds
	s_mov_b32 m0, s52
	s_or_b32 s65, s15, 0x80
	buffer_load_dwordx4 v133, s[56:59], s53 offen lds
	s_add_i32 s53, s7, 0x8000
	s_mov_b32 m0, s53
	s_add_i32 s64, s7, 0xa000
	buffer_load_dwordx4 v130, s[44:47], s65 offen lds
	s_mov_b32 m0, s64
	s_add_i32 s76, s7, 0x1e000
	buffer_load_dwordx4 v132, s[44:47], s65 offen lds
	s_add_i32 s65, s7, 0x1c000
	s_or_b32 s47, s6, 0x80080
	s_mov_b32 m0, s65
	v_mov_b32_e32 v2, 0
	buffer_load_dwordx4 v131, s[56:59], s47 offen lds
	s_mov_b32 m0, s76
	v_lshl_or_b32 v218, s83, 6, v219
	buffer_load_dwordx4 v133, s[56:59], s47 offen lds
	s_waitcnt vmcnt(6)
	s_mov_b32 s67, 0x80080
	s_add_i32 s77, s7, 0xc000
	s_add_i32 s78, s7, 0xe000
	s_mov_b32 s79, -2
	v_add_u32_e32 v134, 0, v3
	v_add_u32_e32 v135, 0, v4
	v_mov_b32_e32 v3, v2
	v_mov_b32_e32 v4, v2
	v_mov_b32_e32 v5, v2
	v_mov_b32_e32 v6, v2
	v_mov_b32_e32 v7, v2
	v_mov_b32_e32 v8, v2
	v_mov_b32_e32 v9, v2
	v_mov_b32_e32 v18, v2
	v_mov_b32_e32 v19, v2
	v_mov_b32_e32 v20, v2
	v_mov_b32_e32 v21, v2
	v_mov_b32_e32 v22, v2
	v_mov_b32_e32 v23, v2
	v_mov_b32_e32 v24, v2
	v_mov_b32_e32 v25, v2
	v_mov_b32_e32 v62, v2
	v_mov_b32_e32 v63, v2
	v_mov_b32_e32 v64, v2
	v_mov_b32_e32 v65, v2
	v_mov_b32_e32 v70, v2
	v_mov_b32_e32 v71, v2
	v_mov_b32_e32 v72, v2
	v_mov_b32_e32 v73, v2
	v_mov_b32_e32 v114, v2
	v_mov_b32_e32 v115, v2
	v_mov_b32_e32 v116, v2
	v_mov_b32_e32 v117, v2
	v_mov_b32_e32 v122, v2
	v_mov_b32_e32 v123, v2
	v_mov_b32_e32 v124, v2
	v_mov_b32_e32 v125, v2
	v_mov_b32_e32 v10, v2
	v_mov_b32_e32 v11, v2
	v_mov_b32_e32 v12, v2
	v_mov_b32_e32 v13, v2
	v_mov_b32_e32 v14, v2
	v_mov_b32_e32 v15, v2
	v_mov_b32_e32 v16, v2
	v_mov_b32_e32 v17, v2
	v_mov_b32_e32 v38, v2
	v_mov_b32_e32 v39, v2
	v_mov_b32_e32 v40, v2
	v_mov_b32_e32 v41, v2
	v_mov_b32_e32 v46, v2
	v_mov_b32_e32 v47, v2
	v_mov_b32_e32 v48, v2
	v_mov_b32_e32 v49, v2
	v_mov_b32_e32 v90, v2
	v_mov_b32_e32 v91, v2
	v_mov_b32_e32 v92, v2
	v_mov_b32_e32 v93, v2
	v_mov_b32_e32 v98, v2
	v_mov_b32_e32 v99, v2
	v_mov_b32_e32 v100, v2
	v_mov_b32_e32 v101, v2
	v_mov_b32_e32 v118, v2
	v_mov_b32_e32 v119, v2
	v_mov_b32_e32 v120, v2
	v_mov_b32_e32 v121, v2
	v_mov_b32_e32 v126, v2
	v_mov_b32_e32 v127, v2
	v_mov_b32_e32 v128, v2
	v_mov_b32_e32 v129, v2
	v_mov_b32_e32 v106, v2
	v_mov_b32_e32 v107, v2
	v_mov_b32_e32 v108, v2
	v_mov_b32_e32 v109, v2
	v_mov_b32_e32 v110, v2
	v_mov_b32_e32 v111, v2
	v_mov_b32_e32 v112, v2
	v_mov_b32_e32 v113, v2
	v_mov_b32_e32 v82, v2
	v_mov_b32_e32 v83, v2
	v_mov_b32_e32 v84, v2
	v_mov_b32_e32 v85, v2
	v_mov_b32_e32 v86, v2
	v_mov_b32_e32 v87, v2
	v_mov_b32_e32 v88, v2
	v_mov_b32_e32 v89, v2
	v_mov_b32_e32 v58, v2
	v_mov_b32_e32 v59, v2
	v_mov_b32_e32 v60, v2
	v_mov_b32_e32 v61, v2
	v_mov_b32_e32 v66, v2
	v_mov_b32_e32 v67, v2
	v_mov_b32_e32 v68, v2
	v_mov_b32_e32 v69, v2
	v_mov_b32_e32 v34, v2
	v_mov_b32_e32 v35, v2
	v_mov_b32_e32 v36, v2
	v_mov_b32_e32 v37, v2
	v_mov_b32_e32 v42, v2
	v_mov_b32_e32 v43, v2
	v_mov_b32_e32 v44, v2
	v_mov_b32_e32 v45, v2
	v_mov_b32_e32 v94, v2
	v_mov_b32_e32 v95, v2
	v_mov_b32_e32 v96, v2
	v_mov_b32_e32 v97, v2
	v_mov_b32_e32 v102, v2
	v_mov_b32_e32 v103, v2
	v_mov_b32_e32 v104, v2
	v_mov_b32_e32 v105, v2
	v_mov_b32_e32 v74, v2
	v_mov_b32_e32 v75, v2
	v_mov_b32_e32 v76, v2
	v_mov_b32_e32 v77, v2
	v_mov_b32_e32 v78, v2
	v_mov_b32_e32 v79, v2
	v_mov_b32_e32 v80, v2
	v_mov_b32_e32 v81, v2
	v_mov_b32_e32 v50, v2
	v_mov_b32_e32 v51, v2
	v_mov_b32_e32 v52, v2
	v_mov_b32_e32 v53, v2
	v_mov_b32_e32 v54, v2
	v_mov_b32_e32 v55, v2
	v_mov_b32_e32 v56, v2
	v_mov_b32_e32 v57, v2
	v_mov_b32_e32 v26, v2
	v_mov_b32_e32 v27, v2
	v_mov_b32_e32 v28, v2
	v_mov_b32_e32 v29, v2
	v_mov_b32_e32 v30, v2
	v_mov_b32_e32 v31, v2
	v_mov_b32_e32 v32, v2
	v_mov_b32_e32 v33, v2
	v_add_u32_e32 v203, 0x10000, v134
	v_add_u32_e32 v204, 0x14000, v134
	v_add_u32_e32 v205, 0x18000, v134
	v_add_u32_e32 v206, 0x1c000, v134
.Lwout_head:
	s_barrier
.LBB0_1161:
	ds_read_b128 v[136:139], v203
	ds_read_b128 v[140:143], v203 offset:1024
	ds_read_b128 v[144:147], v203 offset:2048
	ds_read_b128 v[148:151], v203 offset:3072
	ds_read_b128 v[152:155], v204
	ds_read_b128 v[156:159], v204 offset:1024
	ds_read_b128 v[160:163], v204 offset:2048
	ds_read_b128 v[164:167], v204 offset:3072
	s_add_i32 s47, s67, 0xfff80080
	s_cmp_lg_u32 s79, 28
	s_cselect_b32 s88, s47, 0
	s_add_i32 s89, s88, s15
	s_or_b32 s80, s89, 0x80
	s_add_i32 s88, s88, s6
	s_add_i32 s59, s15, s67
	s_mov_b32 s47, s31
	s_mov_b32 m0, s77
	ds_read_b128 v[168:171], v135
	ds_read_b128 v[172:175], v135 offset:1024
	ds_read_b128 v[176:179], v135 offset:2048
	ds_read_b128 v[180:183], v135 offset:3072
	ds_read_b128 v[184:187], v135 offset:4096
	ds_read_b128 v[188:191], v135 offset:5120
	ds_read_b128 v[192:195], v135 offset:6144
	ds_read_b128 v[196:199], v135 offset:7168
	buffer_load_dwordx4 v130, s[44:47], s59 offen lds
	s_mov_b32 m0, s78
	s_nop 0
	buffer_load_dwordx4 v132, s[44:47], s59 offen lds
	s_waitcnt vmcnt(8)
	s_waitcnt lgkmcnt(0)
	s_barrier
	s_setprio 1
	s_waitcnt lgkmcnt(7)
	v_mfma_f32_16x16x32_bf16 v[30:33], v[136:139], v[168:171], v[30:33]
	v_mfma_f32_16x16x32_bf16 v[26:29], v[144:147], v[168:171], v[26:29]
	s_waitcnt lgkmcnt(5)
	v_mfma_f32_16x16x32_bf16 v[54:57], v[136:139], v[176:179], v[54:57]
	v_mfma_f32_16x16x32_bf16 v[50:53], v[144:147], v[176:179], v[50:53]
	s_waitcnt lgkmcnt(3)
	v_mfma_f32_16x16x32_bf16 v[78:81], v[136:139], v[184:187], v[78:81]
	v_mfma_f32_16x16x32_bf16 v[74:77], v[144:147], v[184:187], v[74:77]
	s_waitcnt lgkmcnt(1)
	v_mfma_f32_16x16x32_bf16 v[102:105], v[136:139], v[192:195], v[102:105]
	v_mfma_f32_16x16x32_bf16 v[94:97], v[144:147], v[192:195], v[94:97]
	v_mfma_f32_16x16x32_bf16 v[30:33], v[140:143], v[172:175], v[30:33]
	v_mfma_f32_16x16x32_bf16 v[26:29], v[148:151], v[172:175], v[26:29]
	v_mfma_f32_16x16x32_bf16 v[54:57], v[140:143], v[180:183], v[54:57]
	v_mfma_f32_16x16x32_bf16 v[50:53], v[148:151], v[180:183], v[50:53]
	v_mfma_f32_16x16x32_bf16 v[78:81], v[140:143], v[188:191], v[78:81]
	v_mfma_f32_16x16x32_bf16 v[74:77], v[148:151], v[188:191], v[74:77]
	s_waitcnt lgkmcnt(0)
	v_mfma_f32_16x16x32_bf16 v[102:105], v[140:143], v[196:199], v[102:105]
	v_mfma_f32_16x16x32_bf16 v[94:97], v[148:151], v[196:199], v[94:97]
	s_setprio 0
	s_setprio 1
	v_mfma_f32_16x16x32_bf16 v[42:45], v[152:155], v[168:171], v[42:45]
	v_mfma_f32_16x16x32_bf16 v[34:37], v[160:163], v[168:171], v[34:37]
	v_mfma_f32_16x16x32_bf16 v[66:69], v[152:155], v[176:179], v[66:69]
	v_mfma_f32_16x16x32_bf16 v[58:61], v[160:163], v[176:179], v[58:61]
	v_mfma_f32_16x16x32_bf16 v[86:89], v[152:155], v[184:187], v[86:89]
	v_mfma_f32_16x16x32_bf16 v[82:85], v[160:163], v[184:187], v[82:85]
	v_mfma_f32_16x16x32_bf16 v[110:113], v[152:155], v[192:195], v[110:113]
	v_mfma_f32_16x16x32_bf16 v[106:109], v[160:163], v[192:195], v[106:109]
	v_mfma_f32_16x16x32_bf16 v[42:45], v[156:159], v[172:175], v[42:45]
	v_mfma_f32_16x16x32_bf16 v[34:37], v[164:167], v[172:175], v[34:37]
	v_mfma_f32_16x16x32_bf16 v[66:69], v[156:159], v[180:183], v[66:69]
	v_mfma_f32_16x16x32_bf16 v[58:61], v[164:167], v[180:183], v[58:61]
	v_mfma_f32_16x16x32_bf16 v[86:89], v[156:159], v[188:191], v[86:89]
	v_mfma_f32_16x16x32_bf16 v[82:85], v[164:167], v[188:191], v[82:85]
	v_mfma_f32_16x16x32_bf16 v[110:113], v[156:159], v[196:199], v[110:113]
	v_mfma_f32_16x16x32_bf16 v[106:109], v[164:167], v[196:199], v[106:109]
	s_setprio 0
	s_barrier
	s_mov_b32 m0, s8
	s_mov_b32 s59, s31
	ds_read_b128 v[168:171], v135 offset:16384
	ds_read_b128 v[172:175], v135 offset:17408
	ds_read_b128 v[176:179], v135 offset:18432
	ds_read_b128 v[180:183], v135 offset:19456
	ds_read_b128 v[184:187], v135 offset:20480
	ds_read_b128 v[188:191], v135 offset:21504
	ds_read_b128 v[192:195], v135 offset:22528
	ds_read_b128 v[196:199], v135 offset:23552
	buffer_load_dwordx4 v131, s[56:59], s88 offen lds
	s_mov_b32 m0, s9
	s_add_i32 s90, s88, 0x80000
	buffer_load_dwordx4 v133, s[56:59], s88 offen lds
	s_mov_b32 m0, s13
	s_nop 0
	buffer_load_dwordx4 v131, s[56:59], s90 offen lds
	s_mov_b32 m0, s14
	s_nop 0
	buffer_load_dwordx4 v133, s[56:59], s90 offen lds
	s_mov_b32 m0, s7
	s_nop 0
	buffer_load_dwordx4 v130, s[44:47], s89 offen lds
	s_mov_b32 m0, s16
	s_nop 0
	buffer_load_dwordx4 v132, s[44:47], s89 offen lds
	s_waitcnt vmcnt(8)
	s_waitcnt lgkmcnt(0)
	s_barrier
	s_setprio 1
	s_waitcnt lgkmcnt(7)
	v_mfma_f32_16x16x32_bf16 v[126:129], v[136:139], v[168:171], v[126:129]
	v_mfma_f32_16x16x32_bf16 v[118:121], v[144:147], v[168:171], v[118:121]
	s_waitcnt lgkmcnt(5)
	v_mfma_f32_16x16x32_bf16 v[98:101], v[136:139], v[176:179], v[98:101]
	v_mfma_f32_16x16x32_bf16 v[90:93], v[144:147], v[176:179], v[90:93]
	s_waitcnt lgkmcnt(3)
	v_mfma_f32_16x16x32_bf16 v[46:49], v[136:139], v[184:187], v[46:49]
	v_mfma_f32_16x16x32_bf16 v[38:41], v[144:147], v[184:187], v[38:41]
	s_waitcnt lgkmcnt(1)
	v_mfma_f32_16x16x32_bf16 v[14:17], v[136:139], v[192:195], v[14:17]
	v_mfma_f32_16x16x32_bf16 v[10:13], v[144:147], v[192:195], v[10:13]
	v_mfma_f32_16x16x32_bf16 v[126:129], v[140:143], v[172:175], v[126:129]
	v_mfma_f32_16x16x32_bf16 v[118:121], v[148:151], v[172:175], v[118:121]
	v_mfma_f32_16x16x32_bf16 v[98:101], v[140:143], v[180:183], v[98:101]
	v_mfma_f32_16x16x32_bf16 v[90:93], v[148:151], v[180:183], v[90:93]
	v_mfma_f32_16x16x32_bf16 v[46:49], v[140:143], v[188:191], v[46:49]
	v_mfma_f32_16x16x32_bf16 v[38:41], v[148:151], v[188:191], v[38:41]
	s_waitcnt lgkmcnt(0)
	v_mfma_f32_16x16x32_bf16 v[14:17], v[140:143], v[196:199], v[14:17]
	v_mfma_f32_16x16x32_bf16 v[10:13], v[148:151], v[196:199], v[10:13]
	s_setprio 0
	s_setprio 1
	v_mfma_f32_16x16x32_bf16 v[122:125], v[152:155], v[168:171], v[122:125]
	v_mfma_f32_16x16x32_bf16 v[114:117], v[160:163], v[168:171], v[114:117]
	v_mfma_f32_16x16x32_bf16 v[70:73], v[152:155], v[176:179], v[70:73]
	v_mfma_f32_16x16x32_bf16 v[62:65], v[160:163], v[176:179], v[62:65]
	v_mfma_f32_16x16x32_bf16 v[22:25], v[152:155], v[184:187], v[22:25]
	v_mfma_f32_16x16x32_bf16 v[18:21], v[160:163], v[184:187], v[18:21]
	v_mfma_f32_16x16x32_bf16 v[6:9], v[152:155], v[192:195], v[6:9]
	v_mfma_f32_16x16x32_bf16 v[2:5], v[160:163], v[192:195], v[2:5]
	v_mfma_f32_16x16x32_bf16 v[122:125], v[156:159], v[172:175], v[122:125]
	v_mfma_f32_16x16x32_bf16 v[114:117], v[164:167], v[172:175], v[114:117]
	v_mfma_f32_16x16x32_bf16 v[70:73], v[156:159], v[180:183], v[70:73]
	v_mfma_f32_16x16x32_bf16 v[62:65], v[164:167], v[180:183], v[62:65]
	v_mfma_f32_16x16x32_bf16 v[22:25], v[156:159], v[188:191], v[22:25]
	v_mfma_f32_16x16x32_bf16 v[18:21], v[164:167], v[188:191], v[18:21]
	v_mfma_f32_16x16x32_bf16 v[6:9], v[156:159], v[196:199], v[6:9]
	v_mfma_f32_16x16x32_bf16 v[2:5], v[164:167], v[196:199], v[2:5]
	s_setprio 0
	s_barrier
	ds_read_b128 v[136:139], v205
	ds_read_b128 v[140:143], v205 offset:1024
	ds_read_b128 v[144:147], v205 offset:2048
	ds_read_b128 v[148:151], v205 offset:3072
	ds_read_b128 v[152:155], v206
	ds_read_b128 v[156:159], v206 offset:1024
	ds_read_b128 v[160:163], v206 offset:2048
	ds_read_b128 v[164:167], v206 offset:3072
	s_add_i32 s89, s89, 0x80000
	s_mov_b32 m0, s17
	ds_read_b128 v[168:171], v135 offset:32768
	ds_read_b128 v[172:175], v135 offset:33792
	ds_read_b128 v[176:179], v135 offset:34816
	ds_read_b128 v[180:183], v135 offset:35840
	ds_read_b128 v[184:187], v135 offset:36864
	ds_read_b128 v[188:191], v135 offset:37888
	ds_read_b128 v[192:195], v135 offset:38912
	ds_read_b128 v[196:199], v135 offset:39936
	buffer_load_dwordx4 v130, s[44:47], s89 offen lds
	s_mov_b32 m0, s18
	s_nop 0
	buffer_load_dwordx4 v132, s[44:47], s89 offen lds
	s_waitcnt vmcnt(8)
	s_waitcnt lgkmcnt(0)
	s_barrier
	s_setprio 1
	s_waitcnt lgkmcnt(7)
	v_mfma_f32_16x16x32_bf16 v[30:33], v[136:139], v[168:171], v[30:33]
	v_mfma_f32_16x16x32_bf16 v[26:29], v[144:147], v[168:171], v[26:29]
	s_waitcnt lgkmcnt(5)
	v_mfma_f32_16x16x32_bf16 v[54:57], v[136:139], v[176:179], v[54:57]
	v_mfma_f32_16x16x32_bf16 v[50:53], v[144:147], v[176:179], v[50:53]
	s_waitcnt lgkmcnt(3)
	v_mfma_f32_16x16x32_bf16 v[78:81], v[136:139], v[184:187], v[78:81]
	v_mfma_f32_16x16x32_bf16 v[74:77], v[144:147], v[184:187], v[74:77]
	s_waitcnt lgkmcnt(1)
	v_mfma_f32_16x16x32_bf16 v[102:105], v[136:139], v[192:195], v[102:105]
	v_mfma_f32_16x16x32_bf16 v[94:97], v[144:147], v[192:195], v[94:97]
	v_mfma_f32_16x16x32_bf16 v[30:33], v[140:143], v[172:175], v[30:33]
	v_mfma_f32_16x16x32_bf16 v[26:29], v[148:151], v[172:175], v[26:29]
	v_mfma_f32_16x16x32_bf16 v[54:57], v[140:143], v[180:183], v[54:57]
	v_mfma_f32_16x16x32_bf16 v[50:53], v[148:151], v[180:183], v[50:53]
	v_mfma_f32_16x16x32_bf16 v[78:81], v[140:143], v[188:191], v[78:81]
	v_mfma_f32_16x16x32_bf16 v[74:77], v[148:151], v[188:191], v[74:77]
	s_waitcnt lgkmcnt(0)
	v_mfma_f32_16x16x32_bf16 v[102:105], v[140:143], v[196:199], v[102:105]
	v_mfma_f32_16x16x32_bf16 v[94:97], v[148:151], v[196:199], v[94:97]
	s_setprio 0
	s_setprio 1
	v_mfma_f32_16x16x32_bf16 v[42:45], v[152:155], v[168:171], v[42:45]
	v_mfma_f32_16x16x32_bf16 v[34:37], v[160:163], v[168:171], v[34:37]
	v_mfma_f32_16x16x32_bf16 v[66:69], v[152:155], v[176:179], v[66:69]
	v_mfma_f32_16x16x32_bf16 v[58:61], v[160:163], v[176:179], v[58:61]
	v_mfma_f32_16x16x32_bf16 v[86:89], v[152:155], v[184:187], v[86:89]
	v_mfma_f32_16x16x32_bf16 v[82:85], v[160:163], v[184:187], v[82:85]
	v_mfma_f32_16x16x32_bf16 v[110:113], v[152:155], v[192:195], v[110:113]
	v_mfma_f32_16x16x32_bf16 v[106:109], v[160:163], v[192:195], v[106:109]
	v_mfma_f32_16x16x32_bf16 v[42:45], v[156:159], v[172:175], v[42:45]
	v_mfma_f32_16x16x32_bf16 v[34:37], v[164:167], v[172:175], v[34:37]
	v_mfma_f32_16x16x32_bf16 v[66:69], v[156:159], v[180:183], v[66:69]
	v_mfma_f32_16x16x32_bf16 v[58:61], v[164:167], v[180:183], v[58:61]
	v_mfma_f32_16x16x32_bf16 v[86:89], v[156:159], v[188:191], v[86:89]
	v_mfma_f32_16x16x32_bf16 v[82:85], v[164:167], v[188:191], v[82:85]
	v_mfma_f32_16x16x32_bf16 v[110:113], v[156:159], v[196:199], v[110:113]
	v_mfma_f32_16x16x32_bf16 v[106:109], v[164:167], v[196:199], v[106:109]
	s_setprio 0
	s_barrier
	s_mov_b32 m0, s19
	s_or_b32 s89, s88, 0x80
	ds_read_b128 v[168:171], v135 offset:49152
	ds_read_b128 v[172:175], v135 offset:50176
	ds_read_b128 v[176:179], v135 offset:51200
	ds_read_b128 v[180:183], v135 offset:52224
	ds_read_b128 v[184:187], v135 offset:53248
	ds_read_b128 v[188:191], v135 offset:54272
	ds_read_b128 v[192:195], v135 offset:55296
	ds_read_b128 v[196:199], v135 offset:56320
	buffer_load_dwordx4 v131, s[56:59], s89 offen lds
	s_mov_b32 m0, s52
	s_add_i32 s88, s88, 0x80080
	buffer_load_dwordx4 v133, s[56:59], s89 offen lds
	s_mov_b32 m0, s65
	s_nop 0
	buffer_load_dwordx4 v131, s[56:59], s88 offen lds
	s_mov_b32 m0, s76
	s_nop 0
	buffer_load_dwordx4 v133, s[56:59], s88 offen lds
	s_mov_b32 m0, s53
	s_nop 0
	buffer_load_dwordx4 v130, s[44:47], s80 offen lds
	s_mov_b32 m0, s64
	s_nop 0
	buffer_load_dwordx4 v132, s[44:47], s80 offen lds
	s_waitcnt vmcnt(8)
	s_waitcnt lgkmcnt(0)
	s_barrier
	s_setprio 1
	s_waitcnt lgkmcnt(7)
	v_mfma_f32_16x16x32_bf16 v[126:129], v[136:139], v[168:171], v[126:129]
	v_mfma_f32_16x16x32_bf16 v[118:121], v[144:147], v[168:171], v[118:121]
	s_waitcnt lgkmcnt(5)
	v_mfma_f32_16x16x32_bf16 v[98:101], v[136:139], v[176:179], v[98:101]
	v_mfma_f32_16x16x32_bf16 v[90:93], v[144:147], v[176:179], v[90:93]
	s_waitcnt lgkmcnt(3)
	v_mfma_f32_16x16x32_bf16 v[46:49], v[136:139], v[184:187], v[46:49]
	v_mfma_f32_16x16x32_bf16 v[38:41], v[144:147], v[184:187], v[38:41]
	s_waitcnt lgkmcnt(1)
	v_mfma_f32_16x16x32_bf16 v[14:17], v[136:139], v[192:195], v[14:17]
	v_mfma_f32_16x16x32_bf16 v[10:13], v[144:147], v[192:195], v[10:13]
	v_mfma_f32_16x16x32_bf16 v[126:129], v[140:143], v[172:175], v[126:129]
	v_mfma_f32_16x16x32_bf16 v[118:121], v[148:151], v[172:175], v[118:121]
	v_mfma_f32_16x16x32_bf16 v[98:101], v[140:143], v[180:183], v[98:101]
	v_mfma_f32_16x16x32_bf16 v[90:93], v[148:151], v[180:183], v[90:93]
	v_mfma_f32_16x16x32_bf16 v[46:49], v[140:143], v[188:191], v[46:49]
	v_mfma_f32_16x16x32_bf16 v[38:41], v[148:151], v[188:191], v[38:41]
	s_waitcnt lgkmcnt(0)
	v_mfma_f32_16x16x32_bf16 v[14:17], v[140:143], v[196:199], v[14:17]
	v_mfma_f32_16x16x32_bf16 v[10:13], v[148:151], v[196:199], v[10:13]
	s_setprio 0
	s_setprio 1
	v_mfma_f32_16x16x32_bf16 v[122:125], v[152:155], v[168:171], v[122:125]
	v_mfma_f32_16x16x32_bf16 v[114:117], v[160:163], v[168:171], v[114:117]
	v_mfma_f32_16x16x32_bf16 v[70:73], v[152:155], v[176:179], v[70:73]
	v_mfma_f32_16x16x32_bf16 v[62:65], v[160:163], v[176:179], v[62:65]
	v_mfma_f32_16x16x32_bf16 v[22:25], v[152:155], v[184:187], v[22:25]
	v_mfma_f32_16x16x32_bf16 v[18:21], v[160:163], v[184:187], v[18:21]
	v_mfma_f32_16x16x32_bf16 v[6:9], v[152:155], v[192:195], v[6:9]
	v_mfma_f32_16x16x32_bf16 v[2:5], v[160:163], v[192:195], v[2:5]
	v_mfma_f32_16x16x32_bf16 v[122:125], v[156:159], v[172:175], v[122:125]
	v_mfma_f32_16x16x32_bf16 v[114:117], v[164:167], v[172:175], v[114:117]
	v_mfma_f32_16x16x32_bf16 v[70:73], v[156:159], v[180:183], v[70:73]
	v_mfma_f32_16x16x32_bf16 v[62:65], v[164:167], v[180:183], v[62:65]
	v_mfma_f32_16x16x32_bf16 v[22:25], v[156:159], v[188:191], v[22:25]
	v_mfma_f32_16x16x32_bf16 v[18:21], v[164:167], v[188:191], v[18:21]
	v_mfma_f32_16x16x32_bf16 v[6:9], v[156:159], v[196:199], v[6:9]
	v_mfma_f32_16x16x32_bf16 v[2:5], v[164:167], v[196:199], v[2:5]
	s_setprio 0
	s_add_i32 s79, s79, 2
	s_addk_i32 s67, 0x100
	s_cmp_lt_u32 s79, 30
	s_cbranch_scc1 .Lwout_head
	s_barrier
	s_waitcnt vmcnt(0)
	s_cmpk_gt_u32 s66, 0xff
	s_cbranch_scc1 .LBB0_1164
	s_barrier
